# ff1 (phase 9) output stores: nt streaming -> sc0 sc1 write-through (keeps lines cache-allocatable for the ff2 A-operand read, no dirty lines at the barrier)
# baseline (speedup 1.0000x reference)
; DI u32x4 pk8(const f32x4& a, const f32x4& b) { u32x4 w; w.x = pk2(a[0], a[1]); w.y = pk2(a[2], a[3]); w.z = pk2(b[0], b[1]); w.w = pk2(b[2], b[3]); return w; }
; template <bool NT = false> DI void st_rows16(void* base, unsigned pitch_b, unsigned row0, unsigned col0, int fr, int fq, const u32x4& w0, const u32x4& w1) {
;   u32x4 x;
; #pragma unroll
;   for (int e = 0; e < 4; ++e) x[e] = (unsigned)__builtin_amdgcn_update_dpp(0, (int)w1[e], 0x128  , 0xf, 0xf, false);
;   const bool hi = fr >= 8;
;   u32x4 pa, pb;
; #pragma unroll
;   for (int e = 0; e < 4; ++e) { pa[e] = hi ? x[e] : w0[e]; pb[e] = hi ? w0[e] : x[e]; }
;   const unsigned ra = row0 + (unsigned)(fr & 7), ca = col0 + 8u * fq + (hi ? 32u : 0u), cb = col0 + 8u * fq + (hi ? 0u : 32u);
;   if (NT) { __builtin_nontemporal_store(pa, (u32x4*)((char*)base + (ra * pitch_b + ca * 2u))); __builtin_nontemporal_store(pb, (u32x4*)((char*)base + ((ra + 8u) * pitch_b + cb * 2u))); }
;   else { gst<u32x4>(base, ra * pitch_b + ca * 2u, pa); gst<u32x4>(base, (ra + 8u) * pitch_b + cb * 2u, pb); }
;   DI void operator()(g8::Acc& acc, int pm, int pn, int wr, int wc, int fr, int fq) const {
;     ...
;       for (int m = 0; m < 4; ++m) {
;         const int row = pm * BM + ai * HALF + wr * 64 + m * 16 + fr; const float rs = rsqrtf(ssq[row] * (1.0f / DM) + RMS_EPS) * sc;
;         u32x4 wv[2];
; #pragma unroll
;         for (int bj = 0; bj < 2; ++bj) {
;           f32x4 o0 = acc[ai][bj][m][0] * rs, o1 = acc[ai][bj][m][1] * rs;
;           if (act) {
; #pragma unroll
;             for (int e = 0; e < 4; ++e) { const float a = fmaxf(o0[e], 0.f), b = fmaxf(o1[e], 0.f); o0[e] = a * a; o1[e] = b * b; } }
;           wv[bj] = pk8(o0, o1);
;         }
;         st_rows16(dst, (unsigned)ld * 2u, (unsigned)(row - fr), (unsigned)(pn * BM + wc * 64), fr, fq, wv[0], wv[1]);
;         __builtin_amdgcn_sched_barrier(0);
.LBB0_763:
	s_lshl_b32 s0, s42, 8
	s_add_i32 s0, s0, s14
	v_or_b32_e32 v150, s0, v140
	v_ashrrev_i32_e32 v151, 31, v150
	v_lshl_add_u64 v[150:151], v[150:151], 2, s[16:17]
	global_load_dword v232, v[150:151], off
	global_load_dword v233, v[150:151], off offset:64
	global_load_dword v234, v[150:151], off offset:128
	global_load_dword v235, v[150:151], off offset:192
	global_load_dword v236, v[150:151], off offset:512
	global_load_dword v237, v[150:151], off offset:576
	global_load_dword v238, v[150:151], off offset:640
	global_load_dword v239, v[150:151], off offset:704
	v_mov_b32_e32 v153, 0
	v_lshl_or_b32 v150, s1, 8, v145
	v_mov_b32_e32 v154, 0
	v_mov_b32_e32 v155, 0
	v_mov_b32_e32 v156, 0
	v_or_b32_e32 v151, v150, v143
	v_or_b32_e32 v157, s0, v142
	v_or_b32_e32 v150, v150, v144
	v_lshlrev_b32_e32 v151, 1, v151
	v_lshlrev_b32_e32 v157, 13, v157
	v_lshlrev_b32_e32 v150, 1, v150
	s_waitcnt vmcnt(0)
	v_fmamk_f32 v152, v232, 0x3a800000, v149
	v_mul_f32_e32 v158, 0x4b800000, v152
	v_cmp_gt_f32_e32 vcc, s21, v152
	s_nop 1
	v_cndmask_b32_e32 v152, v152, v158, vcc
	v_rsq_f32_e32 v152, v152
	v_add_u32_e32 v158, v151, v157
	v_add3_u32 v157, v150, v157, s11
	v_mul_f32_e32 v159, 0x45800000, v152
	v_cndmask_b32_e32 v152, v152, v159, vcc
	v_pk_mul_f32 v[118:119], v[118:119], v[152:153] op_sel_hi:[1,0]
	v_pk_mul_f32 v[116:117], v[116:117], v[152:153] op_sel_hi:[1,0]
	v_pk_mul_f32 v[114:115], v[114:115], v[152:153] op_sel_hi:[1,0]
	v_pk_mul_f32 v[112:113], v[112:113], v[152:153] op_sel_hi:[1,0]
	v_pk_mul_f32 v[126:127], v[126:127], v[152:153] op_sel_hi:[1,0]
	v_pk_mul_f32 v[124:125], v[124:125], v[152:153] op_sel_hi:[1,0]
	v_pk_mul_f32 v[122:123], v[122:123], v[152:153] op_sel_hi:[1,0]
	v_pk_mul_f32 v[120:121], v[120:121], v[152:153] op_sel_hi:[1,0]
	v_max_f32_e32 v116, 0, v116
	v_max_f32_e32 v112, 0, v112
	v_max_f32_e32 v117, 0, v117
	v_max_f32_e32 v113, 0, v113
	v_max_f32_e32 v118, 0, v118
	v_max_f32_e32 v114, 0, v114
	v_max_f32_e32 v119, 0, v119
	v_max_f32_e32 v115, 0, v115
	v_max_f32_e32 v124, 0, v124
	v_max_f32_e32 v120, 0, v120
	v_max_f32_e32 v125, 0, v125
	v_max_f32_e32 v121, 0, v121
	v_max_f32_e32 v126, 0, v126
	v_max_f32_e32 v122, 0, v122
	v_max_f32_e32 v127, 0, v127
	v_max_f32_e32 v123, 0, v123
	v_pk_mul_f32 v[116:117], v[116:117], v[116:117]
	v_pk_mul_f32 v[112:113], v[112:113], v[112:113]
	v_pk_mul_f32 v[118:119], v[118:119], v[118:119]
	v_pk_mul_f32 v[114:115], v[114:115], v[114:115]
	v_pk_mul_f32 v[124:125], v[124:125], v[124:125]
	v_pk_mul_f32 v[120:121], v[120:121], v[120:121]
	v_pk_mul_f32 v[126:127], v[126:127], v[126:127]
	v_pk_mul_f32 v[122:123], v[122:123], v[122:123]
	v_cvt_pk_bf16_f32 v116, v116, v117
	v_cvt_pk_bf16_f32 v117, v118, v119
	v_cvt_pk_bf16_f32 v112, v112, v113
	v_cvt_pk_bf16_f32 v113, v114, v115
	v_cvt_pk_bf16_f32 v124, v124, v125
	v_cvt_pk_bf16_f32 v125, v126, v127
	v_cvt_pk_bf16_f32 v120, v120, v121
	v_cvt_pk_bf16_f32 v121, v122, v123
	v_mov_b32_dpp v153, v116 row_ror:8 row_mask:0xf bank_mask:0xf
	v_mov_b32_dpp v154, v117 row_ror:8 row_mask:0xf bank_mask:0xf
	v_mov_b32_dpp v155, v112 row_ror:8 row_mask:0xf bank_mask:0xf
	v_mov_b32_dpp v156, v113 row_ror:8 row_mask:0xf bank_mask:0xf
	v_cndmask_b32_e64 v112, v124, v153, s[4:5]
	v_cndmask_b32_e64 v113, v125, v154, s[4:5]
	v_cndmask_b32_e64 v114, v120, v155, s[4:5]
	v_cndmask_b32_e64 v115, v121, v156, s[4:5]
	v_cndmask_b32_e64 v116, v153, v124, s[4:5]
	v_cndmask_b32_e64 v117, v154, v125, s[4:5]
	v_cndmask_b32_e64 v118, v155, v120, s[4:5]
	v_cndmask_b32_e64 v119, v156, v121, s[4:5]
	global_store_dwordx4 v158, v[112:115], s[24:25] sc0 sc1
	global_store_dwordx4 v157, v[116:119], s[24:25] sc0 sc1
	s_or_b32 s1, s0, 16
	v_mov_b32_e32 v113, 0
	v_mov_b32_e32 v114, 0
	v_mov_b32_e32 v115, 0
	v_mov_b32_e32 v116, 0
	v_or_b32_e32 v117, s1, v142
	v_lshlrev_b32_e32 v117, 13, v117
	v_fmamk_f32 v112, v233, 0x3a800000, v149
	v_mul_f32_e32 v118, 0x4b800000, v112
	v_cmp_gt_f32_e32 vcc, s21, v112
	s_nop 1
	v_cndmask_b32_e32 v112, v112, v118, vcc
	v_rsq_f32_e32 v112, v112
	v_add_u32_e32 v118, v151, v117
	v_add3_u32 v117, v150, v117, s11
	v_mul_f32_e32 v119, 0x45800000, v112
	v_cndmask_b32_e32 v112, v112, v119, vcc
	v_pk_mul_f32 v[102:103], v[102:103], v[112:113] op_sel_hi:[1,0]
	v_pk_mul_f32 v[100:101], v[100:101], v[112:113] op_sel_hi:[1,0]
	v_pk_mul_f32 v[98:99], v[98:99], v[112:113] op_sel_hi:[1,0]
	v_pk_mul_f32 v[96:97], v[96:97], v[112:113] op_sel_hi:[1,0]
	v_pk_mul_f32 v[110:111], v[110:111], v[112:113] op_sel_hi:[1,0]
	v_pk_mul_f32 v[108:109], v[108:109], v[112:113] op_sel_hi:[1,0]
	v_pk_mul_f32 v[106:107], v[106:107], v[112:113] op_sel_hi:[1,0]
	v_pk_mul_f32 v[104:105], v[104:105], v[112:113] op_sel_hi:[1,0]
	v_max_f32_e32 v100, 0, v100
	v_max_f32_e32 v96, 0, v96
	v_max_f32_e32 v101, 0, v101
	v_max_f32_e32 v97, 0, v97
	v_max_f32_e32 v102, 0, v102
	v_max_f32_e32 v98, 0, v98
	v_max_f32_e32 v103, 0, v103
	v_max_f32_e32 v99, 0, v99
	v_max_f32_e32 v108, 0, v108
	v_max_f32_e32 v104, 0, v104
	v_max_f32_e32 v109, 0, v109
	v_max_f32_e32 v105, 0, v105
	v_max_f32_e32 v110, 0, v110
	v_max_f32_e32 v106, 0, v106
	v_max_f32_e32 v111, 0, v111
	v_max_f32_e32 v107, 0, v107
	v_pk_mul_f32 v[100:101], v[100:101], v[100:101]
	v_pk_mul_f32 v[96:97], v[96:97], v[96:97]
	v_pk_mul_f32 v[102:103], v[102:103], v[102:103]
	v_pk_mul_f32 v[98:99], v[98:99], v[98:99]
	v_pk_mul_f32 v[108:109], v[108:109], v[108:109]
	v_pk_mul_f32 v[104:105], v[104:105], v[104:105]
	v_pk_mul_f32 v[110:111], v[110:111], v[110:111]
	v_pk_mul_f32 v[106:107], v[106:107], v[106:107]
	v_cvt_pk_bf16_f32 v100, v100, v101
	v_cvt_pk_bf16_f32 v101, v102, v103
	v_cvt_pk_bf16_f32 v96, v96, v97
	v_cvt_pk_bf16_f32 v97, v98, v99
; DI u32x4 pk8(const f32x4& a, const f32x4& b) { u32x4 w; w.x = pk2(a[0], a[1]); w.y = pk2(a[2], a[3]); w.z = pk2(b[0], b[1]); w.w = pk2(b[2], b[3]); return w; }
; template <bool NT = false> DI void st_rows16(void* base, unsigned pitch_b, unsigned row0, unsigned col0, int fr, int fq, const u32x4& w0, const u32x4& w1) {
;   u32x4 x;
; #pragma unroll
;   for (int e = 0; e < 4; ++e) x[e] = (unsigned)__builtin_amdgcn_update_dpp(0, (int)w1[e], 0x128  , 0xf, 0xf, false);
;   const bool hi = fr >= 8;
;   u32x4 pa, pb;
; #pragma unroll
;   for (int e = 0; e < 4; ++e) { pa[e] = hi ? x[e] : w0[e]; pb[e] = hi ? w0[e] : x[e]; }
;   const unsigned ra = row0 + (unsigned)(fr & 7), ca = col0 + 8u * fq + (hi ? 32u : 0u), cb = col0 + 8u * fq + (hi ? 0u : 32u);
;   if (NT) { __builtin_nontemporal_store(pa, (u32x4*)((char*)base + (ra * pitch_b + ca * 2u))); __builtin_nontemporal_store(pb, (u32x4*)((char*)base + ((ra + 8u) * pitch_b + cb * 2u))); }
;   else { gst<u32x4>(base, ra * pitch_b + ca * 2u, pa); gst<u32x4>(base, (ra + 8u) * pitch_b + cb * 2u, pb); }
;   DI void operator()(g8::Acc& acc, int pm, int pn, int wr, int wc, int fr, int fq) const {
;     ...
;       for (int m = 0; m < 4; ++m) {
;         const int row = pm * BM + ai * HALF + wr * 64 + m * 16 + fr; const float rs = rsqrtf(ssq[row] * (1.0f / DM) + RMS_EPS) * sc;
;         u32x4 wv[2];
; #pragma unroll
;         for (int bj = 0; bj < 2; ++bj) {
;           f32x4 o0 = acc[ai][bj][m][0] * rs, o1 = acc[ai][bj][m][1] * rs;
;           if (act) {
; #pragma unroll
;             for (int e = 0; e < 4; ++e) { const float a = fmaxf(o0[e], 0.f), b = fmaxf(o1[e], 0.f); o0[e] = a * a; o1[e] = b * b; } }
;           wv[bj] = pk8(o0, o1);
;         }
;         st_rows16(dst, (unsigned)ld * 2u, (unsigned)(row - fr), (unsigned)(pn * BM + wc * 64), fr, fq, wv[0], wv[1]);
;         __builtin_amdgcn_sched_barrier(0);
	v_cvt_pk_bf16_f32 v108, v108, v109
	v_cvt_pk_bf16_f32 v109, v110, v111
	v_cvt_pk_bf16_f32 v104, v104, v105
	v_cvt_pk_bf16_f32 v105, v106, v107
	v_mov_b32_dpp v113, v100 row_ror:8 row_mask:0xf bank_mask:0xf
	v_mov_b32_dpp v114, v101 row_ror:8 row_mask:0xf bank_mask:0xf
	v_mov_b32_dpp v115, v96 row_ror:8 row_mask:0xf bank_mask:0xf
	v_mov_b32_dpp v116, v97 row_ror:8 row_mask:0xf bank_mask:0xf
	v_cndmask_b32_e64 v96, v108, v113, s[4:5]
	v_cndmask_b32_e64 v97, v109, v114, s[4:5]
	v_cndmask_b32_e64 v98, v104, v115, s[4:5]
	v_cndmask_b32_e64 v99, v105, v116, s[4:5]
	v_cndmask_b32_e64 v100, v113, v108, s[4:5]
	v_cndmask_b32_e64 v101, v114, v109, s[4:5]
	v_cndmask_b32_e64 v102, v115, v104, s[4:5]
	v_cndmask_b32_e64 v103, v116, v105, s[4:5]
	global_store_dwordx4 v118, v[96:99], s[24:25] sc0 sc1
	global_store_dwordx4 v117, v[100:103], s[24:25] sc0 sc1
	s_or_b32 s1, s0, 32
	v_mov_b32_e32 v97, 0
	v_mov_b32_e32 v98, 0
	v_mov_b32_e32 v99, 0
	v_mov_b32_e32 v100, 0
	v_or_b32_e32 v101, s1, v142
	v_lshlrev_b32_e32 v101, 13, v101
	v_fmamk_f32 v96, v234, 0x3a800000, v149
	v_mul_f32_e32 v102, 0x4b800000, v96
	v_cmp_gt_f32_e32 vcc, s21, v96
	s_nop 1
	v_cndmask_b32_e32 v96, v96, v102, vcc
	v_rsq_f32_e32 v96, v96
	v_add_u32_e32 v102, v151, v101
	v_add3_u32 v101, v150, v101, s11
	v_mul_f32_e32 v103, 0x45800000, v96
	v_cndmask_b32_e32 v96, v96, v103, vcc
	v_pk_mul_f32 v[86:87], v[86:87], v[96:97] op_sel_hi:[1,0]
	v_pk_mul_f32 v[84:85], v[84:85], v[96:97] op_sel_hi:[1,0]
	v_pk_mul_f32 v[82:83], v[82:83], v[96:97] op_sel_hi:[1,0]
	v_pk_mul_f32 v[80:81], v[80:81], v[96:97] op_sel_hi:[1,0]
	v_pk_mul_f32 v[94:95], v[94:95], v[96:97] op_sel_hi:[1,0]
	v_pk_mul_f32 v[92:93], v[92:93], v[96:97] op_sel_hi:[1,0]
	v_pk_mul_f32 v[90:91], v[90:91], v[96:97] op_sel_hi:[1,0]
	v_pk_mul_f32 v[88:89], v[88:89], v[96:97] op_sel_hi:[1,0]
	v_max_f32_e32 v84, 0, v84
	v_max_f32_e32 v80, 0, v80
	v_max_f32_e32 v85, 0, v85
	v_max_f32_e32 v81, 0, v81
	v_max_f32_e32 v86, 0, v86
	v_max_f32_e32 v82, 0, v82
	v_max_f32_e32 v87, 0, v87
	v_max_f32_e32 v83, 0, v83
	v_max_f32_e32 v92, 0, v92
	v_max_f32_e32 v88, 0, v88
	v_max_f32_e32 v93, 0, v93
	v_max_f32_e32 v89, 0, v89
	v_max_f32_e32 v94, 0, v94
	v_max_f32_e32 v90, 0, v90
	v_max_f32_e32 v95, 0, v95
	v_max_f32_e32 v91, 0, v91
	v_pk_mul_f32 v[84:85], v[84:85], v[84:85]
	v_pk_mul_f32 v[80:81], v[80:81], v[80:81]
	v_pk_mul_f32 v[86:87], v[86:87], v[86:87]
	v_pk_mul_f32 v[82:83], v[82:83], v[82:83]
	v_pk_mul_f32 v[92:93], v[92:93], v[92:93]
	v_pk_mul_f32 v[88:89], v[88:89], v[88:89]
	v_pk_mul_f32 v[94:95], v[94:95], v[94:95]
	v_pk_mul_f32 v[90:91], v[90:91], v[90:91]
	v_cvt_pk_bf16_f32 v84, v84, v85
	v_cvt_pk_bf16_f32 v85, v86, v87
	v_cvt_pk_bf16_f32 v80, v80, v81
	v_cvt_pk_bf16_f32 v81, v82, v83
	v_cvt_pk_bf16_f32 v92, v92, v93
	v_cvt_pk_bf16_f32 v93, v94, v95
	v_cvt_pk_bf16_f32 v88, v88, v89
	v_cvt_pk_bf16_f32 v89, v90, v91
	v_mov_b32_dpp v97, v84 row_ror:8 row_mask:0xf bank_mask:0xf
	v_mov_b32_dpp v98, v85 row_ror:8 row_mask:0xf bank_mask:0xf
	v_mov_b32_dpp v99, v80 row_ror:8 row_mask:0xf bank_mask:0xf
	v_mov_b32_dpp v100, v81 row_ror:8 row_mask:0xf bank_mask:0xf
	v_cndmask_b32_e64 v80, v92, v97, s[4:5]
	v_cndmask_b32_e64 v81, v93, v98, s[4:5]
	v_cndmask_b32_e64 v82, v88, v99, s[4:5]
	v_cndmask_b32_e64 v83, v89, v100, s[4:5]
	v_cndmask_b32_e64 v84, v97, v92, s[4:5]
	v_cndmask_b32_e64 v85, v98, v93, s[4:5]
	v_cndmask_b32_e64 v86, v99, v88, s[4:5]
	v_cndmask_b32_e64 v87, v100, v89, s[4:5]
	global_store_dwordx4 v102, v[80:83], s[24:25] sc0 sc1
	global_store_dwordx4 v101, v[84:87], s[24:25] sc0 sc1
	s_or_b32 s1, s0, 48
	v_mov_b32_e32 v81, 0
	v_mov_b32_e32 v82, 0
	v_mov_b32_e32 v83, 0
	v_mov_b32_e32 v84, 0
	v_or_b32_e32 v85, s1, v142
	v_lshlrev_b32_e32 v85, 13, v85
	v_fmamk_f32 v80, v235, 0x3a800000, v149
	v_mul_f32_e32 v86, 0x4b800000, v80
	v_cmp_gt_f32_e32 vcc, s21, v80
	s_nop 1
	v_cndmask_b32_e32 v80, v80, v86, vcc
	v_rsq_f32_e32 v80, v80
	v_add_u32_e32 v86, v151, v85
	v_add3_u32 v85, v150, v85, s11
	v_mul_f32_e32 v87, 0x45800000, v80
	v_cndmask_b32_e32 v80, v80, v87, vcc
	v_pk_mul_f32 v[70:71], v[70:71], v[80:81] op_sel_hi:[1,0]
	v_pk_mul_f32 v[68:69], v[68:69], v[80:81] op_sel_hi:[1,0]
	v_pk_mul_f32 v[66:67], v[66:67], v[80:81] op_sel_hi:[1,0]
	v_pk_mul_f32 v[64:65], v[64:65], v[80:81] op_sel_hi:[1,0]
	v_pk_mul_f32 v[78:79], v[78:79], v[80:81] op_sel_hi:[1,0]
	v_pk_mul_f32 v[76:77], v[76:77], v[80:81] op_sel_hi:[1,0]
	v_pk_mul_f32 v[74:75], v[74:75], v[80:81] op_sel_hi:[1,0]
	v_pk_mul_f32 v[72:73], v[72:73], v[80:81] op_sel_hi:[1,0]
	v_max_f32_e32 v68, 0, v68
	v_max_f32_e32 v64, 0, v64
	v_max_f32_e32 v69, 0, v69
	v_max_f32_e32 v65, 0, v65
	v_max_f32_e32 v70, 0, v70
	v_max_f32_e32 v66, 0, v66
	v_max_f32_e32 v71, 0, v71
	v_max_f32_e32 v67, 0, v67
	v_max_f32_e32 v76, 0, v76
	v_max_f32_e32 v72, 0, v72
	v_max_f32_e32 v77, 0, v77
	v_max_f32_e32 v73, 0, v73
	v_max_f32_e32 v78, 0, v78
	v_max_f32_e32 v74, 0, v74
	v_max_f32_e32 v79, 0, v79
	v_max_f32_e32 v75, 0, v75
	v_pk_mul_f32 v[68:69], v[68:69], v[68:69]
	v_pk_mul_f32 v[64:65], v[64:65], v[64:65]
	v_pk_mul_f32 v[70:71], v[70:71], v[70:71]
	v_pk_mul_f32 v[66:67], v[66:67], v[66:67]
	v_pk_mul_f32 v[76:77], v[76:77], v[76:77]
	v_pk_mul_f32 v[72:73], v[72:73], v[72:73]
	v_pk_mul_f32 v[78:79], v[78:79], v[78:79]
	v_pk_mul_f32 v[74:75], v[74:75], v[74:75]
	v_cvt_pk_bf16_f32 v68, v68, v69
	v_cvt_pk_bf16_f32 v69, v70, v71
	v_cvt_pk_bf16_f32 v64, v64, v65
	v_cvt_pk_bf16_f32 v65, v66, v67
	v_cvt_pk_bf16_f32 v76, v76, v77
	v_cvt_pk_bf16_f32 v77, v78, v79
	v_cvt_pk_bf16_f32 v72, v72, v73
	v_cvt_pk_bf16_f32 v73, v74, v75
	v_mov_b32_dpp v81, v68 row_ror:8 row_mask:0xf bank_mask:0xf
	v_mov_b32_dpp v82, v69 row_ror:8 row_mask:0xf bank_mask:0xf
; DI u32x4 pk8(const f32x4& a, const f32x4& b) { u32x4 w; w.x = pk2(a[0], a[1]); w.y = pk2(a[2], a[3]); w.z = pk2(b[0], b[1]); w.w = pk2(b[2], b[3]); return w; }
; template <bool NT = false> DI void st_rows16(void* base, unsigned pitch_b, unsigned row0, unsigned col0, int fr, int fq, const u32x4& w0, const u32x4& w1) {
;   u32x4 x;
; #pragma unroll
;   for (int e = 0; e < 4; ++e) x[e] = (unsigned)__builtin_amdgcn_update_dpp(0, (int)w1[e], 0x128  , 0xf, 0xf, false);
;   const bool hi = fr >= 8;
;   u32x4 pa, pb;
; #pragma unroll
;   for (int e = 0; e < 4; ++e) { pa[e] = hi ? x[e] : w0[e]; pb[e] = hi ? w0[e] : x[e]; }
;   const unsigned ra = row0 + (unsigned)(fr & 7), ca = col0 + 8u * fq + (hi ? 32u : 0u), cb = col0 + 8u * fq + (hi ? 0u : 32u);
;   if (NT) { __builtin_nontemporal_store(pa, (u32x4*)((char*)base + (ra * pitch_b + ca * 2u))); __builtin_nontemporal_store(pb, (u32x4*)((char*)base + ((ra + 8u) * pitch_b + cb * 2u))); }
;   else { gst<u32x4>(base, ra * pitch_b + ca * 2u, pa); gst<u32x4>(base, (ra + 8u) * pitch_b + cb * 2u, pb); }
;   DI void operator()(g8::Acc& acc, int pm, int pn, int wr, int wc, int fr, int fq) const {
;     ...
;       for (int m = 0; m < 4; ++m) {
;         const int row = pm * BM + ai * HALF + wr * 64 + m * 16 + fr; const float rs = rsqrtf(ssq[row] * (1.0f / DM) + RMS_EPS) * sc;
;         u32x4 wv[2];
; #pragma unroll
;         for (int bj = 0; bj < 2; ++bj) {
;           f32x4 o0 = acc[ai][bj][m][0] * rs, o1 = acc[ai][bj][m][1] * rs;
;           if (act) {
; #pragma unroll
;             for (int e = 0; e < 4; ++e) { const float a = fmaxf(o0[e], 0.f), b = fmaxf(o1[e], 0.f); o0[e] = a * a; o1[e] = b * b; } }
;           wv[bj] = pk8(o0, o1);
;         }
;         st_rows16(dst, (unsigned)ld * 2u, (unsigned)(row - fr), (unsigned)(pn * BM + wc * 64), fr, fq, wv[0], wv[1]);
;         __builtin_amdgcn_sched_barrier(0);
	v_mov_b32_dpp v83, v64 row_ror:8 row_mask:0xf bank_mask:0xf
	v_mov_b32_dpp v84, v65 row_ror:8 row_mask:0xf bank_mask:0xf
	v_cndmask_b32_e64 v64, v76, v81, s[4:5]
	v_cndmask_b32_e64 v65, v77, v82, s[4:5]
	v_cndmask_b32_e64 v66, v72, v83, s[4:5]
	v_cndmask_b32_e64 v67, v73, v84, s[4:5]
	v_cndmask_b32_e64 v68, v81, v76, s[4:5]
	v_cndmask_b32_e64 v69, v82, v77, s[4:5]
	v_cndmask_b32_e64 v70, v83, v72, s[4:5]
	v_cndmask_b32_e64 v71, v84, v73, s[4:5]
	global_store_dwordx4 v86, v[64:67], s[24:25] sc0 sc1
	global_store_dwordx4 v85, v[68:71], s[24:25] sc0 sc1
	s_add_i32 s1, s0, 0x80
	v_mov_b32_e32 v65, 0
	v_mov_b32_e32 v66, 0
	v_mov_b32_e32 v67, 0
	v_mov_b32_e32 v68, 0
	v_or_b32_e32 v69, s1, v142
	v_lshlrev_b32_e32 v69, 13, v69
	v_fmamk_f32 v64, v236, 0x3a800000, v149
	v_mul_f32_e32 v70, 0x4b800000, v64
	v_cmp_gt_f32_e32 vcc, s21, v64
	s_nop 1
	v_cndmask_b32_e32 v64, v64, v70, vcc
	v_rsq_f32_e32 v64, v64
	v_add_u32_e32 v70, v151, v69
	v_add3_u32 v69, v150, v69, s11
	v_mul_f32_e32 v71, 0x45800000, v64
	v_cndmask_b32_e32 v64, v64, v71, vcc
	v_pk_mul_f32 v[54:55], v[54:55], v[64:65] op_sel_hi:[1,0]
	v_pk_mul_f32 v[52:53], v[52:53], v[64:65] op_sel_hi:[1,0]
	v_pk_mul_f32 v[50:51], v[50:51], v[64:65] op_sel_hi:[1,0]
	v_pk_mul_f32 v[48:49], v[48:49], v[64:65] op_sel_hi:[1,0]
	v_pk_mul_f32 v[62:63], v[62:63], v[64:65] op_sel_hi:[1,0]
	v_pk_mul_f32 v[60:61], v[60:61], v[64:65] op_sel_hi:[1,0]
	v_pk_mul_f32 v[58:59], v[58:59], v[64:65] op_sel_hi:[1,0]
	v_pk_mul_f32 v[56:57], v[56:57], v[64:65] op_sel_hi:[1,0]
	v_max_f32_e32 v52, 0, v52
	v_max_f32_e32 v48, 0, v48
	v_max_f32_e32 v53, 0, v53
	v_max_f32_e32 v49, 0, v49
	v_max_f32_e32 v54, 0, v54
	v_max_f32_e32 v50, 0, v50
	v_max_f32_e32 v55, 0, v55
	v_max_f32_e32 v51, 0, v51
	v_max_f32_e32 v60, 0, v60
	v_max_f32_e32 v56, 0, v56
	v_max_f32_e32 v61, 0, v61
	v_max_f32_e32 v57, 0, v57
	v_max_f32_e32 v62, 0, v62
	v_max_f32_e32 v58, 0, v58
	v_max_f32_e32 v63, 0, v63
	v_max_f32_e32 v59, 0, v59
	v_pk_mul_f32 v[52:53], v[52:53], v[52:53]
	v_pk_mul_f32 v[48:49], v[48:49], v[48:49]
	v_pk_mul_f32 v[54:55], v[54:55], v[54:55]
	v_pk_mul_f32 v[50:51], v[50:51], v[50:51]
	v_pk_mul_f32 v[60:61], v[60:61], v[60:61]
	v_pk_mul_f32 v[56:57], v[56:57], v[56:57]
	v_pk_mul_f32 v[62:63], v[62:63], v[62:63]
	v_pk_mul_f32 v[58:59], v[58:59], v[58:59]
	v_cvt_pk_bf16_f32 v52, v52, v53
	v_cvt_pk_bf16_f32 v53, v54, v55
	v_cvt_pk_bf16_f32 v48, v48, v49
	v_cvt_pk_bf16_f32 v49, v50, v51
	v_cvt_pk_bf16_f32 v60, v60, v61
	v_cvt_pk_bf16_f32 v61, v62, v63
	v_cvt_pk_bf16_f32 v56, v56, v57
	v_cvt_pk_bf16_f32 v57, v58, v59
	v_mov_b32_dpp v65, v52 row_ror:8 row_mask:0xf bank_mask:0xf
	v_mov_b32_dpp v66, v53 row_ror:8 row_mask:0xf bank_mask:0xf
	v_mov_b32_dpp v67, v48 row_ror:8 row_mask:0xf bank_mask:0xf
	v_mov_b32_dpp v68, v49 row_ror:8 row_mask:0xf bank_mask:0xf
	v_cndmask_b32_e64 v48, v60, v65, s[4:5]
	v_cndmask_b32_e64 v49, v61, v66, s[4:5]
	v_cndmask_b32_e64 v50, v56, v67, s[4:5]
	v_cndmask_b32_e64 v51, v57, v68, s[4:5]
	v_cndmask_b32_e64 v52, v65, v60, s[4:5]
	v_cndmask_b32_e64 v53, v66, v61, s[4:5]
	v_cndmask_b32_e64 v54, v67, v56, s[4:5]
	v_cndmask_b32_e64 v55, v68, v57, s[4:5]
	global_store_dwordx4 v70, v[48:51], s[24:25] sc0 sc1
	global_store_dwordx4 v69, v[52:55], s[24:25] sc0 sc1
	s_add_i32 s1, s0, 0x90
	v_mov_b32_e32 v49, 0
	v_mov_b32_e32 v50, 0
	v_mov_b32_e32 v51, 0
	v_mov_b32_e32 v52, 0
	v_or_b32_e32 v53, s1, v142
	v_lshlrev_b32_e32 v53, 13, v53
	v_fmamk_f32 v48, v237, 0x3a800000, v149
	v_mul_f32_e32 v54, 0x4b800000, v48
	v_cmp_gt_f32_e32 vcc, s21, v48
	s_nop 1
	v_cndmask_b32_e32 v48, v48, v54, vcc
	v_rsq_f32_e32 v48, v48
	v_add_u32_e32 v54, v151, v53
	v_add3_u32 v53, v150, v53, s11
	v_mul_f32_e32 v55, 0x45800000, v48
	v_cndmask_b32_e32 v48, v48, v55, vcc
	v_pk_mul_f32 v[38:39], v[38:39], v[48:49] op_sel_hi:[1,0]
	v_pk_mul_f32 v[36:37], v[36:37], v[48:49] op_sel_hi:[1,0]
	v_pk_mul_f32 v[34:35], v[34:35], v[48:49] op_sel_hi:[1,0]
	v_pk_mul_f32 v[32:33], v[32:33], v[48:49] op_sel_hi:[1,0]
	v_pk_mul_f32 v[46:47], v[46:47], v[48:49] op_sel_hi:[1,0]
	v_pk_mul_f32 v[44:45], v[44:45], v[48:49] op_sel_hi:[1,0]
	v_pk_mul_f32 v[42:43], v[42:43], v[48:49] op_sel_hi:[1,0]
	v_pk_mul_f32 v[40:41], v[40:41], v[48:49] op_sel_hi:[1,0]
	v_max_f32_e32 v36, 0, v36
	v_max_f32_e32 v32, 0, v32
	v_max_f32_e32 v37, 0, v37
	v_max_f32_e32 v33, 0, v33
	v_max_f32_e32 v38, 0, v38
	v_max_f32_e32 v34, 0, v34
	v_max_f32_e32 v39, 0, v39
	v_max_f32_e32 v35, 0, v35
	v_max_f32_e32 v44, 0, v44
	v_max_f32_e32 v40, 0, v40
	v_max_f32_e32 v45, 0, v45
	v_max_f32_e32 v41, 0, v41
	v_max_f32_e32 v46, 0, v46
	v_max_f32_e32 v42, 0, v42
	v_max_f32_e32 v47, 0, v47
	v_max_f32_e32 v43, 0, v43
	v_pk_mul_f32 v[36:37], v[36:37], v[36:37]
	v_pk_mul_f32 v[32:33], v[32:33], v[32:33]
	v_pk_mul_f32 v[38:39], v[38:39], v[38:39]
	v_pk_mul_f32 v[34:35], v[34:35], v[34:35]
	v_pk_mul_f32 v[44:45], v[44:45], v[44:45]
	v_pk_mul_f32 v[40:41], v[40:41], v[40:41]
	v_pk_mul_f32 v[46:47], v[46:47], v[46:47]
	v_pk_mul_f32 v[42:43], v[42:43], v[42:43]
	v_cvt_pk_bf16_f32 v36, v36, v37
	v_cvt_pk_bf16_f32 v37, v38, v39
	v_cvt_pk_bf16_f32 v32, v32, v33
	v_cvt_pk_bf16_f32 v33, v34, v35
	v_cvt_pk_bf16_f32 v44, v44, v45
	v_cvt_pk_bf16_f32 v45, v46, v47
	v_cvt_pk_bf16_f32 v40, v40, v41
	v_cvt_pk_bf16_f32 v41, v42, v43
	v_mov_b32_dpp v49, v36 row_ror:8 row_mask:0xf bank_mask:0xf
	v_mov_b32_dpp v50, v37 row_ror:8 row_mask:0xf bank_mask:0xf
	v_mov_b32_dpp v51, v32 row_ror:8 row_mask:0xf bank_mask:0xf
	v_mov_b32_dpp v52, v33 row_ror:8 row_mask:0xf bank_mask:0xf
	v_cndmask_b32_e64 v32, v44, v49, s[4:5]
	v_cndmask_b32_e64 v33, v45, v50, s[4:5]
	v_cndmask_b32_e64 v34, v40, v51, s[4:5]
	v_cndmask_b32_e64 v35, v41, v52, s[4:5]
; DI u32x4 pk8(const f32x4& a, const f32x4& b) { u32x4 w; w.x = pk2(a[0], a[1]); w.y = pk2(a[2], a[3]); w.z = pk2(b[0], b[1]); w.w = pk2(b[2], b[3]); return w; }
; template <bool NT = false> DI void st_rows16(void* base, unsigned pitch_b, unsigned row0, unsigned col0, int fr, int fq, const u32x4& w0, const u32x4& w1) {
;   u32x4 x;
; #pragma unroll
;   for (int e = 0; e < 4; ++e) x[e] = (unsigned)__builtin_amdgcn_update_dpp(0, (int)w1[e], 0x128  , 0xf, 0xf, false);
;   const bool hi = fr >= 8;
;   u32x4 pa, pb;
; #pragma unroll
;   for (int e = 0; e < 4; ++e) { pa[e] = hi ? x[e] : w0[e]; pb[e] = hi ? w0[e] : x[e]; }
;   const unsigned ra = row0 + (unsigned)(fr & 7), ca = col0 + 8u * fq + (hi ? 32u : 0u), cb = col0 + 8u * fq + (hi ? 0u : 32u);
;   if (NT) { __builtin_nontemporal_store(pa, (u32x4*)((char*)base + (ra * pitch_b + ca * 2u))); __builtin_nontemporal_store(pb, (u32x4*)((char*)base + ((ra + 8u) * pitch_b + cb * 2u))); }
;   else { gst<u32x4>(base, ra * pitch_b + ca * 2u, pa); gst<u32x4>(base, (ra + 8u) * pitch_b + cb * 2u, pb); }
;   DI void operator()(g8::Acc& acc, int pm, int pn, int wr, int wc, int fr, int fq) const {
;     ...
;       for (int m = 0; m < 4; ++m) {
;         const int row = pm * BM + ai * HALF + wr * 64 + m * 16 + fr; const float rs = rsqrtf(ssq[row] * (1.0f / DM) + RMS_EPS) * sc;
;         u32x4 wv[2];
; #pragma unroll
;         for (int bj = 0; bj < 2; ++bj) {
;           f32x4 o0 = acc[ai][bj][m][0] * rs, o1 = acc[ai][bj][m][1] * rs;
;           if (act) {
; #pragma unroll
;             for (int e = 0; e < 4; ++e) { const float a = fmaxf(o0[e], 0.f), b = fmaxf(o1[e], 0.f); o0[e] = a * a; o1[e] = b * b; } }
;           wv[bj] = pk8(o0, o1);
;         }
;         st_rows16(dst, (unsigned)ld * 2u, (unsigned)(row - fr), (unsigned)(pn * BM + wc * 64), fr, fq, wv[0], wv[1]);
;         __builtin_amdgcn_sched_barrier(0);
	v_cndmask_b32_e64 v36, v49, v44, s[4:5]
	v_cndmask_b32_e64 v37, v50, v45, s[4:5]
	v_cndmask_b32_e64 v38, v51, v40, s[4:5]
	v_cndmask_b32_e64 v39, v52, v41, s[4:5]
	global_store_dwordx4 v54, v[32:35], s[24:25] sc0 sc1
	global_store_dwordx4 v53, v[36:39], s[24:25] sc0 sc1
	s_add_i32 s1, s0, 0xa0
	v_mov_b32_e32 v33, 0
	v_mov_b32_e32 v34, 0
	v_mov_b32_e32 v35, 0
	v_mov_b32_e32 v36, 0
	v_or_b32_e32 v37, s1, v142
	v_lshlrev_b32_e32 v37, 13, v37
	v_fmamk_f32 v32, v238, 0x3a800000, v149
	v_mul_f32_e32 v38, 0x4b800000, v32
	v_cmp_gt_f32_e32 vcc, s21, v32
	s_nop 1
	v_cndmask_b32_e32 v32, v32, v38, vcc
	v_rsq_f32_e32 v32, v32
	v_add_u32_e32 v38, v151, v37
	v_add3_u32 v37, v150, v37, s11
	v_mul_f32_e32 v39, 0x45800000, v32
	v_cndmask_b32_e32 v32, v32, v39, vcc
	v_pk_mul_f32 v[22:23], v[22:23], v[32:33] op_sel_hi:[1,0]
	v_pk_mul_f32 v[20:21], v[20:21], v[32:33] op_sel_hi:[1,0]
	v_pk_mul_f32 v[18:19], v[18:19], v[32:33] op_sel_hi:[1,0]
	v_pk_mul_f32 v[16:17], v[16:17], v[32:33] op_sel_hi:[1,0]
	v_pk_mul_f32 v[30:31], v[30:31], v[32:33] op_sel_hi:[1,0]
	v_pk_mul_f32 v[28:29], v[28:29], v[32:33] op_sel_hi:[1,0]
	v_pk_mul_f32 v[26:27], v[26:27], v[32:33] op_sel_hi:[1,0]
	v_pk_mul_f32 v[24:25], v[24:25], v[32:33] op_sel_hi:[1,0]
	v_max_f32_e32 v20, 0, v20
	v_max_f32_e32 v16, 0, v16
	v_max_f32_e32 v21, 0, v21
	v_max_f32_e32 v17, 0, v17
	v_max_f32_e32 v22, 0, v22
	v_max_f32_e32 v18, 0, v18
	v_max_f32_e32 v23, 0, v23
	v_max_f32_e32 v19, 0, v19
	v_max_f32_e32 v28, 0, v28
	v_max_f32_e32 v24, 0, v24
	v_max_f32_e32 v29, 0, v29
	v_max_f32_e32 v25, 0, v25
	v_max_f32_e32 v30, 0, v30
	v_max_f32_e32 v26, 0, v26
	v_max_f32_e32 v31, 0, v31
	v_max_f32_e32 v27, 0, v27
	v_pk_mul_f32 v[20:21], v[20:21], v[20:21]
	v_pk_mul_f32 v[16:17], v[16:17], v[16:17]
	v_pk_mul_f32 v[22:23], v[22:23], v[22:23]
	v_pk_mul_f32 v[18:19], v[18:19], v[18:19]
	v_pk_mul_f32 v[28:29], v[28:29], v[28:29]
	v_pk_mul_f32 v[24:25], v[24:25], v[24:25]
	v_pk_mul_f32 v[30:31], v[30:31], v[30:31]
	v_pk_mul_f32 v[26:27], v[26:27], v[26:27]
	v_cvt_pk_bf16_f32 v20, v20, v21
	v_cvt_pk_bf16_f32 v21, v22, v23
	v_cvt_pk_bf16_f32 v16, v16, v17
	v_cvt_pk_bf16_f32 v17, v18, v19
	v_cvt_pk_bf16_f32 v28, v28, v29
	v_cvt_pk_bf16_f32 v29, v30, v31
	v_cvt_pk_bf16_f32 v24, v24, v25
	v_cvt_pk_bf16_f32 v25, v26, v27
	v_mov_b32_dpp v33, v20 row_ror:8 row_mask:0xf bank_mask:0xf
	v_mov_b32_dpp v34, v21 row_ror:8 row_mask:0xf bank_mask:0xf
	v_mov_b32_dpp v35, v16 row_ror:8 row_mask:0xf bank_mask:0xf
	v_mov_b32_dpp v36, v17 row_ror:8 row_mask:0xf bank_mask:0xf
	v_cndmask_b32_e64 v16, v28, v33, s[4:5]
	v_cndmask_b32_e64 v17, v29, v34, s[4:5]
	v_cndmask_b32_e64 v18, v24, v35, s[4:5]
	v_cndmask_b32_e64 v19, v25, v36, s[4:5]
	v_cndmask_b32_e64 v20, v33, v28, s[4:5]
	v_cndmask_b32_e64 v21, v34, v29, s[4:5]
	v_cndmask_b32_e64 v22, v35, v24, s[4:5]
	v_cndmask_b32_e64 v23, v36, v25, s[4:5]
	global_store_dwordx4 v38, v[16:19], s[24:25] sc0 sc1
	global_store_dwordx4 v37, v[20:23], s[24:25] sc0 sc1
	s_addk_i32 s0, 0xb0
	v_mov_b32_e32 v17, 0
	v_mov_b32_e32 v18, 0
	v_mov_b32_e32 v19, 0
	v_mov_b32_e32 v20, 0
	v_or_b32_e32 v21, s0, v142
	v_lshlrev_b32_e32 v21, 13, v21
	v_fmamk_f32 v16, v239, 0x3a800000, v149
	v_mul_f32_e32 v22, 0x4b800000, v16
	v_cmp_gt_f32_e32 vcc, s21, v16
	s_nop 1
	v_cndmask_b32_e32 v16, v16, v22, vcc
	v_rsq_f32_e32 v16, v16
	v_add_u32_e32 v22, v151, v21
	v_add3_u32 v21, v150, v21, s11
	v_mul_f32_e32 v23, 0x45800000, v16
	v_cndmask_b32_e32 v16, v16, v23, vcc
	v_pk_mul_f32 v[6:7], v[6:7], v[16:17] op_sel_hi:[1,0]
	v_pk_mul_f32 v[4:5], v[4:5], v[16:17] op_sel_hi:[1,0]
	v_pk_mul_f32 v[2:3], v[2:3], v[16:17] op_sel_hi:[1,0]
	v_pk_mul_f32 v[0:1], v[0:1], v[16:17] op_sel_hi:[1,0]
	v_pk_mul_f32 v[14:15], v[14:15], v[16:17] op_sel_hi:[1,0]
	v_pk_mul_f32 v[12:13], v[12:13], v[16:17] op_sel_hi:[1,0]
	v_pk_mul_f32 v[10:11], v[10:11], v[16:17] op_sel_hi:[1,0]
	v_pk_mul_f32 v[8:9], v[8:9], v[16:17] op_sel_hi:[1,0]
	v_max_f32_e32 v4, 0, v4
	v_max_f32_e32 v0, 0, v0
	v_max_f32_e32 v5, 0, v5
	v_max_f32_e32 v1, 0, v1
	v_max_f32_e32 v6, 0, v6
	v_max_f32_e32 v2, 0, v2
	v_max_f32_e32 v7, 0, v7
	v_max_f32_e32 v3, 0, v3
	v_max_f32_e32 v12, 0, v12
	v_max_f32_e32 v8, 0, v8
	v_max_f32_e32 v13, 0, v13
	v_max_f32_e32 v9, 0, v9
	v_max_f32_e32 v14, 0, v14
	v_max_f32_e32 v10, 0, v10
	v_max_f32_e32 v15, 0, v15
	v_max_f32_e32 v11, 0, v11
	v_pk_mul_f32 v[4:5], v[4:5], v[4:5]
	v_pk_mul_f32 v[0:1], v[0:1], v[0:1]
	v_pk_mul_f32 v[6:7], v[6:7], v[6:7]
	v_pk_mul_f32 v[2:3], v[2:3], v[2:3]
	v_pk_mul_f32 v[12:13], v[12:13], v[12:13]
	v_pk_mul_f32 v[8:9], v[8:9], v[8:9]
	v_pk_mul_f32 v[14:15], v[14:15], v[14:15]
	v_pk_mul_f32 v[10:11], v[10:11], v[10:11]
	v_cvt_pk_bf16_f32 v4, v4, v5
	v_cvt_pk_bf16_f32 v5, v6, v7
	v_cvt_pk_bf16_f32 v0, v0, v1
	v_cvt_pk_bf16_f32 v1, v2, v3
	v_cvt_pk_bf16_f32 v10, v10, v11
	v_cvt_pk_bf16_f32 v8, v8, v9
	v_cvt_pk_bf16_f32 v9, v14, v15
	v_cvt_pk_bf16_f32 v11, v12, v13
	v_mov_b32_dpp v17, v4 row_ror:8 row_mask:0xf bank_mask:0xf
	v_mov_b32_dpp v18, v5 row_ror:8 row_mask:0xf bank_mask:0xf
	v_mov_b32_dpp v19, v0 row_ror:8 row_mask:0xf bank_mask:0xf
	v_mov_b32_dpp v20, v1 row_ror:8 row_mask:0xf bank_mask:0xf
	v_cndmask_b32_e64 v0, v11, v17, s[4:5]
	v_cndmask_b32_e64 v1, v9, v18, s[4:5]
	v_cndmask_b32_e64 v2, v8, v19, s[4:5]
	v_cndmask_b32_e64 v3, v10, v20, s[4:5]
	v_cndmask_b32_e64 v4, v17, v11, s[4:5]
	v_cndmask_b32_e64 v5, v18, v9, s[4:5]
	v_cndmask_b32_e64 v6, v19, v8, s[4:5]
	v_cndmask_b32_e64 v7, v20, v10, s[4:5]
	global_store_dwordx4 v22, v[0:3], s[24:25] sc0 sc1
	global_store_dwordx4 v21, v[4:7], s[24:25] sc0 sc1
	s_andn2_b64 vcc, exec, s[36:37]
	s_mov_b64 s[0:1], -1
	s_cbranch_vccnz .LBB0_756
	s_andn2_b64 vcc, exec, s[6:7]
	s_cbranch_vccnz .LBB0_755
	s_barrier
	s_branch .LBB0_755
